# attention softmax+PV block hand-rescheduled: V fragments prefetched 5 deep via ds_read_b64 pairs, exp in place, no pk_mov shuffles
# speedup vs baseline: 1.0092x; 1.0092x over previous
; __global__ void __launch_bounds__(512, 2) mk_fwd(Args args) {
;     extern __shared__ __attribute__((aligned(16))) unsigned char lds_raw[];
;     ldsp lds = (ldsp)lds_raw;
;     cg::grid_group grid = cg::this_grid();
;     const int tid = threadIdx.x, lane = tid & 63, wave = __builtin_amdgcn_readfirstlane(tid >> 6);
;     const int G = gridDim.x, bx = blockIdx.x, vcu = (G % 8 == 0) ? (bx % 8) * (G / 8) + bx / 8 : bx;
_Z6mk_fwd4Args:
	s_mov_b32 s98, 0
	s_load_dwordx8 s[52:59], s[0:1], 0xa0
	s_load_dwordx8 s[60:67], s[0:1], 0x80
	s_load_dwordx2 s[4:5], s[0:1], 0xc0
	s_add_u32 s10, s0, 0xc0
	s_addc_u32 s11, s1, 0
	v_and_b32_e32 v192, 0x3ff, v0
	s_mov_b32 s73, s2
	s_waitcnt lgkmcnt(0)
	v_writelane_b32 v255, s4, 0
	v_readfirstlane_b32 s3, v192
	s_nop 0
	v_writelane_b32 v255, s5, 1
	s_and_b32 s4, s4, 7
	s_cmp_lg_u32 s4, 0
	s_cbranch_scc1 .LBB0_2
	s_load_dwordx2 s[4:5], s[0:1], 0xc0
	s_waitcnt lgkmcnt(0)
	s_ashr_i32 s5, s2, 31
	s_lshr_b32 s5, s5, 29
	s_add_i32 s5, s2, s5
	s_and_b32 s6, s5, -8
	s_ashr_i32 s4, s4, 3
	s_sub_i32 s6, s2, s6
	s_mul_i32 s4, s4, s6
	s_ashr_i32 s5, s5, 3
	s_add_i32 s73, s4, s5

; #define LAS __attribute__((address_space(3)))
; #define MFMA32(a, b, c) __builtin_amdgcn_mfma_f32_32x32x16_bf16((a), (b), (c), 0, 0, 0)
; DI void attn_phase(ldsp lds, const bf16_t* Q, const bf16_t* KN, const bf16_t* KR, const bf16_t* VT, bf16_t* O, int vcu, int G) {
;     ...
;                     ldsp kb = Lb + l31 * AT_KP + hh * 16;
;                     bf16x8 kf[6];
; #pragma unroll
;                     for (int i = 0; i < 6; ++i) kf[i] = *(const LAS bf16x8*)(kb + (i & 1) * 32 * AT_KP + (i >> 1) * 32);
; #pragma unroll
;                     for (int i = 0; i < 24; ++i) { const bf16x8 cur = kf[i % 6];
;                         if (i + 6 < 24) kf[i % 6] = *(const LAS bf16x8*)(kb + ((i + 6) & 1) * 32 * AT_KP + ((i + 6) >> 1) * 32);
;                         if (i & 1) s1 = MFMA32(cur, qf[i >> 1], s1); else s0 = MFMA32(cur, qf[i >> 1], s0); }
;     ...
;                             for (int d = 0; d < 4; ++d) {
;                                 const bf16x8 va = lds_8x2(Lb + AT_VOFF + (d * 32 + l31) * AT_VP + (kb2 * 32 + 16 * s2 + 4 * hh) * 2, 16);
;                                 o[d] = MFMA32(va, pa[kb2][s2], o[d]); }
.LBB0_1454:
	s_mul_i32 s28, s27, 0xa800
	s_add_i32 s28, s28, 0
	v_add3_u32 v1, s28, v171, v170
	ds_read_b128 v[66:69], v1 offset:12800
	ds_read_b128 v[70:73], v1
	ds_read_b128 v[230:233], v1 offset:32
	ds_read_b128 v[234:237], v1 offset:12832
	ds_read_b128 v[238:241], v1 offset:64
	ds_read_b128 v[242:245], v1 offset:12864
	s_add_i32 s29, s6, 63
	s_cmp_le_i32 s29, s14
	s_waitcnt lgkmcnt(4)
	v_mfma_f32_32x32x16_bf16 v[82:97], v[70:73], v[98:101], 0
	ds_read_b128 v[246:249], v1 offset:96
	v_mfma_f32_32x32x16_bf16 v[66:81], v[66:69], v[98:101], 0
	ds_read_b128 v[250:253], v1 offset:12896
	s_waitcnt lgkmcnt(5)
	v_mfma_f32_32x32x16_bf16 v[82:97], v[230:233], v[102:105], v[82:97]
	ds_read_b128 v[230:233], v1 offset:128
	s_waitcnt lgkmcnt(5)
	v_mfma_f32_32x32x16_bf16 v[66:81], v[234:237], v[102:105], v[66:81]
	ds_read_b128 v[234:237], v1 offset:12928
	s_waitcnt lgkmcnt(5)
	v_mfma_f32_32x32x16_bf16 v[82:97], v[238:241], v[110:113], v[82:97]
	ds_read_b128 v[238:241], v1 offset:160
	s_waitcnt lgkmcnt(5)
	v_mfma_f32_32x32x16_bf16 v[66:81], v[242:245], v[110:113], v[66:81]
	ds_read_b128 v[242:245], v1 offset:12960
	s_waitcnt lgkmcnt(5)
	v_mfma_f32_32x32x16_bf16 v[82:97], v[246:249], v[114:117], v[82:97]
	ds_read_b128 v[246:249], v1 offset:192
	s_waitcnt lgkmcnt(5)
	v_mfma_f32_32x32x16_bf16 v[66:81], v[250:253], v[114:117], v[66:81]
	ds_read_b128 v[250:253], v1 offset:12992
	s_waitcnt lgkmcnt(5)
	v_mfma_f32_32x32x16_bf16 v[82:97], v[230:233], v[122:125], v[82:97]
	ds_read_b128 v[230:233], v1 offset:224
	s_waitcnt lgkmcnt(5)
	v_mfma_f32_32x32x16_bf16 v[66:81], v[234:237], v[122:125], v[66:81]
	ds_read_b128 v[234:237], v1 offset:13024
	s_waitcnt lgkmcnt(5)
	v_mfma_f32_32x32x16_bf16 v[82:97], v[238:241], v[126:129], v[82:97]
	ds_read_b128 v[238:241], v1 offset:256
	s_waitcnt lgkmcnt(5)
	v_mfma_f32_32x32x16_bf16 v[66:81], v[242:245], v[126:129], v[66:81]
	ds_read_b128 v[242:245], v1 offset:13056
	s_waitcnt lgkmcnt(5)
	v_mfma_f32_32x32x16_bf16 v[82:97], v[246:249], v[130:133], v[82:97]
	ds_read_b128 v[246:249], v1 offset:288
	s_waitcnt lgkmcnt(5)
	v_mfma_f32_32x32x16_bf16 v[66:81], v[250:253], v[130:133], v[66:81]
	ds_read_b128 v[250:253], v1 offset:13088
	s_waitcnt lgkmcnt(5)
	v_mfma_f32_32x32x16_bf16 v[82:97], v[230:233], v[138:141], v[82:97]
	ds_read_b128 v[230:233], v1 offset:320
	s_waitcnt lgkmcnt(5)
	v_mfma_f32_32x32x16_bf16 v[66:81], v[234:237], v[138:141], v[66:81]
	ds_read_b128 v[234:237], v1 offset:13120
	s_waitcnt lgkmcnt(5)
	v_mfma_f32_32x32x16_bf16 v[82:97], v[238:241], v[142:145], v[82:97]
	ds_read_b128 v[238:241], v1 offset:352
	s_waitcnt lgkmcnt(5)
	v_mfma_f32_32x32x16_bf16 v[66:81], v[242:245], v[142:145], v[66:81]
	ds_read_b128 v[242:245], v1 offset:13152
	s_waitcnt lgkmcnt(5)
	v_mfma_f32_32x32x16_bf16 v[82:97], v[246:249], v[146:149], v[82:97]
	s_waitcnt lgkmcnt(4)
	v_mfma_f32_32x32x16_bf16 v[66:81], v[250:253], v[146:149], v[66:81]
	s_waitcnt lgkmcnt(3)
	v_mfma_f32_32x32x16_bf16 v[82:97], v[230:233], v[150:153], v[82:97]
	s_waitcnt lgkmcnt(2)
	v_mfma_f32_32x32x16_bf16 v[66:81], v[234:237], v[150:153], v[66:81]
	s_waitcnt lgkmcnt(1)
	v_mfma_f32_32x32x16_bf16 v[82:97], v[238:241], v[154:157], v[82:97]
	s_waitcnt lgkmcnt(0)
	v_mfma_f32_32x32x16_bf16 v[66:81], v[242:245], v[154:157], v[66:81]
	v_add3_u32 v253, s28, v168, v169
	ds_read_b64 v[232:233], v253 offset:25600
	ds_read_b64 v[234:235], v253 offset:25616
	ds_read_b64 v[236:237], v253 offset:29952
	ds_read_b64 v[238:239], v253 offset:29968
	ds_read_b64 v[240:241], v253 offset:34304
	ds_read_b64 v[242:243], v253 offset:34320
	ds_read_b64 v[244:245], v253 offset:38656
	ds_read_b64 v[246:247], v253 offset:38672
	ds_read_b64 v[248:249], v253 offset:25632
	ds_read_b64 v[250:251], v253 offset:25648
	s_cbranch_scc1 .LBB0_1456
; DI int crow(int reg, int hh) { return (reg & 3) + 8 * (reg >> 2) + 4 * hh; }
; DI void attn_phase(ldsp lds, const bf16_t* Q, const bf16_t* KN, const bf16_t* KR, const bf16_t* VT, bf16_t* O, int vcu, int G) {
;     ...
;                     if (key0 + 63 > q0) {
;                         const int qpos = q0 + l31;
; #pragma unroll
;                         for (int r = 0; r < 16; ++r) { const int key = key0 + crow(r, hh); if (key > qpos) s0[r] = -1e30f; if (key + 32 > qpos) s1[r] = -1e30f; }
;                     }
	v_add_u32_e32 v1, s6, v183
	v_add_u32_e32 v230, 32, v1
	v_cmp_le_i32_e32 vcc, v230, v228
	v_add_u32_e32 v230, 33, v1
	s_nop 6
	v_cndmask_b32_e32 v66, v226, v66, vcc
	v_cmp_lt_i32_e32 vcc, v1, v228
	s_nop 1
	v_cndmask_b32_e32 v83, v226, v83, vcc
	v_cmp_le_i32_e32 vcc, v1, v228
	s_nop 1
	v_cndmask_b32_e32 v82, v226, v82, vcc
	v_cmp_le_i32_e32 vcc, v230, v228
	v_add_u32_e32 v230, 2, v1
	s_nop 0
	v_cndmask_b32_e32 v67, v226, v67, vcc
	v_cmp_le_i32_e32 vcc, v230, v228
	v_add_u32_e32 v230, 34, v1
	s_nop 0
	v_cndmask_b32_e32 v84, v226, v84, vcc
	v_cmp_le_i32_e32 vcc, v230, v228
	v_add_u32_e32 v230, 3, v1
	s_nop 0
	v_cndmask_b32_e32 v68, v226, v68, vcc
	v_cmp_le_i32_e32 vcc, v230, v228
	v_add_u32_e32 v230, 35, v1
	s_nop 0
	v_cndmask_b32_e32 v85, v226, v85, vcc
	v_cmp_le_i32_e32 vcc, v230, v228
	v_add_u32_e32 v230, 8, v1
	s_nop 0
	v_cndmask_b32_e32 v69, v226, v69, vcc
	v_cmp_le_i32_e32 vcc, v230, v228
	v_add_u32_e32 v230, 40, v1
	s_nop 0
	v_cndmask_b32_e32 v86, v226, v86, vcc
	v_cmp_le_i32_e32 vcc, v230, v228
	v_add_u32_e32 v230, 9, v1
	s_nop 0
	v_cndmask_b32_e32 v70, v226, v70, vcc
	v_cmp_le_i32_e32 vcc, v230, v228
	v_add_u32_e32 v230, 41, v1
	s_nop 0
	v_cndmask_b32_e32 v87, v226, v87, vcc
	v_cmp_le_i32_e32 vcc, v230, v228
	v_add_u32_e32 v230, 10, v1
	s_nop 0
	v_cndmask_b32_e32 v71, v226, v71, vcc
	v_cmp_le_i32_e32 vcc, v230, v228
	v_add_u32_e32 v230, 42, v1
	s_nop 0
	v_cndmask_b32_e32 v88, v226, v88, vcc
	v_cmp_le_i32_e32 vcc, v230, v228
	v_add_u32_e32 v230, 11, v1
	s_nop 0
	v_cndmask_b32_e32 v72, v226, v72, vcc
	v_cmp_le_i32_e32 vcc, v230, v228
	v_add_u32_e32 v230, 43, v1
	s_nop 0
	v_cndmask_b32_e32 v89, v226, v89, vcc
	v_cmp_le_i32_e32 vcc, v230, v228
	v_add_u32_e32 v230, 16, v1
	s_nop 0
	v_cndmask_b32_e32 v73, v226, v73, vcc
	v_cmp_le_i32_e32 vcc, v230, v228
	v_add_u32_e32 v230, 48, v1
	s_nop 0
	v_cndmask_b32_e32 v90, v226, v90, vcc
	v_cmp_le_i32_e32 vcc, v230, v228
	v_add_u32_e32 v230, 17, v1
	s_nop 0
	v_cndmask_b32_e32 v74, v226, v74, vcc
	v_cmp_le_i32_e32 vcc, v230, v228
	v_add_u32_e32 v230, 49, v1
	s_nop 0
	v_cndmask_b32_e32 v91, v226, v91, vcc
	v_cmp_le_i32_e32 vcc, v230, v228
	v_add_u32_e32 v230, 18, v1
	s_nop 0
	v_cndmask_b32_e32 v75, v226, v75, vcc
	v_cmp_le_i32_e32 vcc, v230, v228
	v_add_u32_e32 v230, 50, v1
	s_nop 0
	v_cndmask_b32_e32 v92, v226, v92, vcc
	v_cmp_le_i32_e32 vcc, v230, v228
	v_add_u32_e32 v230, 19, v1
	s_nop 0
	v_cndmask_b32_e32 v76, v226, v76, vcc
	v_cmp_le_i32_e32 vcc, v230, v228
	v_add_u32_e32 v230, 51, v1
	s_nop 0
	v_cndmask_b32_e32 v93, v226, v93, vcc
	v_cmp_le_i32_e32 vcc, v230, v228
	v_add_u32_e32 v230, 24, v1
	s_nop 0
	v_cndmask_b32_e32 v77, v226, v77, vcc
	v_cmp_le_i32_e32 vcc, v230, v228
	v_add_u32_e32 v230, 56, v1
	s_nop 0
	v_cndmask_b32_e32 v94, v226, v94, vcc
	v_cmp_le_i32_e32 vcc, v230, v228
	v_add_u32_e32 v230, 25, v1
	s_nop 0
	v_cndmask_b32_e32 v78, v226, v78, vcc
	v_cmp_le_i32_e32 vcc, v230, v228
	v_add_u32_e32 v230, 57, v1
	s_nop 0
	v_cndmask_b32_e32 v95, v226, v95, vcc
	v_cmp_le_i32_e32 vcc, v230, v228
	v_add_u32_e32 v230, 26, v1
	s_nop 0
	v_cndmask_b32_e32 v79, v226, v79, vcc
	v_cmp_le_i32_e32 vcc, v230, v228
	v_add_u32_e32 v230, 58, v1
	s_nop 0
	v_cndmask_b32_e32 v96, v226, v96, vcc
	v_cmp_le_i32_e32 vcc, v230, v228
	v_add_u32_e32 v230, 27, v1
	v_add_u32_e32 v1, 59, v1
	v_cndmask_b32_e32 v80, v226, v80, vcc
	v_cmp_le_i32_e32 vcc, v230, v228
	s_nop 1
	v_cndmask_b32_e32 v97, v226, v97, vcc
	v_cmp_le_i32_e32 vcc, v1, v228
	s_nop 1
	v_cndmask_b32_e32 v81, v226, v81, vcc

; #define MFMA32(a, b, c) __builtin_amdgcn_mfma_f32_32x32x16_bf16((a), (b), (c), 0, 0, 0)
; DI void attn_phase(ldsp lds, const bf16_t* Q, const bf16_t* KN, const bf16_t* KR, const bf16_t* VT, bf16_t* O, int vcu, int G) {
;     ...
;                     float rs = 0.f;
; #pragma unroll
;                     for (int r = 0; r < 16; ++r) { s0[r] = __builtin_amdgcn_exp2f(s0[r] - mrun); s1[r] = __builtin_amdgcn_exp2f(s1[r] - mrun); rs += s0[r] + s1[r]; }
;                     lrun += rs;
;                     bf16x8 pa[2][2];
;                     pa[0][0] = pack8(s0, 0); pa[0][1] = pack8(s0, 1); pa[1][0] = pack8(s1, 0); pa[1][1] = pack8(s1, 1);
; #pragma unroll
;                     for (int kb2 = 0; kb2 < 2; ++kb2)
; #pragma unroll
;                         for (int s2 = 0; s2 < 2; ++s2)
; #pragma unroll
;                             for (int d = 0; d < 4; ++d) {
;                                 const bf16x8 va = lds_8x2(Lb + AT_VOFF + (d * 32 + l31) * AT_VP + (kb2 * 32 + 16 * s2 + 4 * hh) * 2, 16);
;                                 o[d] = MFMA32(va, pa[kb2][s2], o[d]); }
.LBB0_1458:
	v_sub_f32_e32 v82, v82, v229
	v_sub_f32_e32 v83, v83, v229
	v_sub_f32_e32 v84, v84, v229
	v_sub_f32_e32 v85, v85, v229
	v_sub_f32_e32 v86, v86, v229
	v_sub_f32_e32 v87, v87, v229
	v_sub_f32_e32 v88, v88, v229
	v_sub_f32_e32 v89, v89, v229
	v_exp_f32_e32 v82, v82
	v_exp_f32_e32 v83, v83
	v_exp_f32_e32 v84, v84
	v_exp_f32_e32 v85, v85
	v_exp_f32_e32 v86, v86
	v_exp_f32_e32 v87, v87
	v_exp_f32_e32 v88, v88
	v_exp_f32_e32 v89, v89
	v_add_f32_e32 v1, v82, v84
	v_add_f32_e32 v230, v83, v85
	v_add_f32_e32 v1, v1, v86
	v_add_f32_e32 v230, v230, v87
	v_add_f32_e32 v1, v1, v88
	v_add_f32_e32 v230, v230, v89
	v_cvt_pk_bf16_f32 v82, v82, v83
	v_cvt_pk_bf16_f32 v83, v84, v85
	v_cvt_pk_bf16_f32 v84, v86, v87
	v_cvt_pk_bf16_f32 v85, v88, v89
	s_nop 1
	s_waitcnt lgkmcnt(8)
	v_mfma_f32_32x32x16_bf16 v[50:65], v[232:235], v[82:85], v[50:65]
	ds_read_b64 v[232:233], v253 offset:29984
	ds_read_b64 v[234:235], v253 offset:30000
	v_sub_f32_e32 v90, v90, v229
	v_sub_f32_e32 v91, v91, v229
	v_sub_f32_e32 v92, v92, v229
	v_sub_f32_e32 v93, v93, v229
	v_sub_f32_e32 v94, v94, v229
	v_sub_f32_e32 v95, v95, v229
	v_sub_f32_e32 v96, v96, v229
	s_waitcnt lgkmcnt(8)
	v_mfma_f32_32x32x16_bf16 v[34:49], v[236:239], v[82:85], v[34:49]
	ds_read_b64 v[236:237], v253 offset:34336
	ds_read_b64 v[238:239], v253 offset:34352
	v_sub_f32_e32 v97, v97, v229
	v_exp_f32_e32 v90, v90
	v_exp_f32_e32 v91, v91
	v_exp_f32_e32 v92, v92
	v_exp_f32_e32 v93, v93
	v_exp_f32_e32 v94, v94
	v_exp_f32_e32 v95, v95
	s_waitcnt lgkmcnt(8)
	v_mfma_f32_32x32x16_bf16 v[18:33], v[240:243], v[82:85], v[18:33]
	ds_read_b64 v[240:241], v253 offset:38688
	ds_read_b64 v[242:243], v253 offset:38704
	v_exp_f32_e32 v96, v96
	v_exp_f32_e32 v97, v97
	v_add_f32_e32 v1, v1, v90
	v_add_f32_e32 v230, v230, v91
	v_add_f32_e32 v1, v1, v92
	v_add_f32_e32 v230, v230, v93
	v_add_f32_e32 v1, v1, v94
	s_waitcnt lgkmcnt(8)
	v_mfma_f32_32x32x16_bf16 v[2:17], v[244:247], v[82:85], v[2:17]
	ds_read_b64 v[244:245], v253 offset:25664
	ds_read_b64 v[246:247], v253 offset:25680
	v_add_f32_e32 v230, v230, v95
	v_add_f32_e32 v1, v1, v96
	v_add_f32_e32 v230, v230, v97
	v_cvt_pk_bf16_f32 v90, v90, v91
	v_cvt_pk_bf16_f32 v91, v92, v93
	v_cvt_pk_bf16_f32 v92, v94, v95
	v_cvt_pk_bf16_f32 v93, v96, v97
	s_nop 1
	s_waitcnt lgkmcnt(8)
	v_mfma_f32_32x32x16_bf16 v[50:65], v[248:251], v[90:93], v[50:65]
	ds_read_b64 v[248:249], v253 offset:30016
	ds_read_b64 v[250:251], v253 offset:30032
	v_sub_f32_e32 v66, v66, v229
	v_sub_f32_e32 v67, v67, v229
	v_sub_f32_e32 v68, v68, v229
	v_sub_f32_e32 v69, v69, v229
	v_sub_f32_e32 v70, v70, v229
	v_sub_f32_e32 v71, v71, v229
	v_sub_f32_e32 v72, v72, v229
	s_waitcnt lgkmcnt(8)
	v_mfma_f32_32x32x16_bf16 v[34:49], v[232:235], v[90:93], v[34:49]
	ds_read_b64 v[232:233], v253 offset:34368
	ds_read_b64 v[234:235], v253 offset:34384
	v_sub_f32_e32 v73, v73, v229
	v_exp_f32_e32 v66, v66
	v_exp_f32_e32 v67, v67
	v_exp_f32_e32 v68, v68
	v_exp_f32_e32 v69, v69
	v_exp_f32_e32 v70, v70
	v_exp_f32_e32 v71, v71
	s_waitcnt lgkmcnt(8)
	v_mfma_f32_32x32x16_bf16 v[18:33], v[236:239], v[90:93], v[18:33]
	ds_read_b64 v[236:237], v253 offset:38720
	ds_read_b64 v[238:239], v253 offset:38736
	v_exp_f32_e32 v72, v72
	v_exp_f32_e32 v73, v73
	v_add_f32_e32 v1, v1, v66
	v_add_f32_e32 v230, v230, v67
	v_add_f32_e32 v1, v1, v68
	v_add_f32_e32 v230, v230, v69
	v_add_f32_e32 v1, v1, v70
	s_waitcnt lgkmcnt(8)
	v_mfma_f32_32x32x16_bf16 v[2:17], v[240:243], v[90:93], v[2:17]
	ds_read_b64 v[240:241], v253 offset:25696
	ds_read_b64 v[242:243], v253 offset:25712
	v_add_f32_e32 v230, v230, v71
	v_add_f32_e32 v1, v1, v72
	v_add_f32_e32 v230, v230, v73
	v_cvt_pk_bf16_f32 v66, v66, v67
	v_cvt_pk_bf16_f32 v67, v68, v69
	v_cvt_pk_bf16_f32 v68, v70, v71
	v_cvt_pk_bf16_f32 v69, v72, v73
	s_nop 1
	s_waitcnt lgkmcnt(8)
	v_mfma_f32_32x32x16_bf16 v[50:65], v[244:247], v[66:69], v[50:65]
	ds_read_b64 v[244:245], v253 offset:30048
	ds_read_b64 v[246:247], v253 offset:30064
	v_sub_f32_e32 v74, v74, v229
	v_sub_f32_e32 v75, v75, v229
	v_sub_f32_e32 v76, v76, v229
	v_sub_f32_e32 v77, v77, v229
	v_sub_f32_e32 v78, v78, v229
	v_sub_f32_e32 v79, v79, v229
	v_sub_f32_e32 v80, v80, v229
	s_waitcnt lgkmcnt(8)
	v_mfma_f32_32x32x16_bf16 v[34:49], v[248:251], v[66:69], v[34:49]
	ds_read_b64 v[248:249], v253 offset:34400
	ds_read_b64 v[250:251], v253 offset:34416
	v_sub_f32_e32 v81, v81, v229
	v_exp_f32_e32 v74, v74
	v_exp_f32_e32 v75, v75
	v_exp_f32_e32 v76, v76
	v_exp_f32_e32 v77, v77
	v_exp_f32_e32 v78, v78
	v_exp_f32_e32 v79, v79
	s_waitcnt lgkmcnt(8)
	v_mfma_f32_32x32x16_bf16 v[18:33], v[232:235], v[66:69], v[18:33]
	ds_read_b64 v[232:233], v253 offset:38752
	ds_read_b64 v[234:235], v253 offset:38768
	v_exp_f32_e32 v80, v80
	v_exp_f32_e32 v81, v81
	v_add_f32_e32 v1, v1, v74
	v_add_f32_e32 v230, v230, v75
	v_add_f32_e32 v1, v1, v76
	v_add_f32_e32 v230, v230, v77
	v_add_f32_e32 v1, v1, v78
	s_waitcnt lgkmcnt(8)
	v_mfma_f32_32x32x16_bf16 v[2:17], v[236:239], v[66:69], v[2:17]
	v_add_f32_e32 v230, v230, v79
	v_add_f32_e32 v1, v1, v80
	v_add_f32_e32 v230, v230, v81
	v_cvt_pk_bf16_f32 v74, v74, v75
	v_cvt_pk_bf16_f32 v75, v76, v77
	v_cvt_pk_bf16_f32 v76, v78, v79
	v_cvt_pk_bf16_f32 v77, v80, v81
	s_nop 1
	s_waitcnt lgkmcnt(6)
	v_mfma_f32_32x32x16_bf16 v[50:65], v[240:243], v[74:77], v[50:65]
	s_waitcnt lgkmcnt(4)
	v_mfma_f32_32x32x16_bf16 v[34:49], v[244:247], v[74:77], v[34:49]
	s_waitcnt lgkmcnt(2)
	v_mfma_f32_32x32x16_bf16 v[18:33], v[248:251], v[74:77], v[18:33]
	s_waitcnt lgkmcnt(0)
	v_mfma_f32_32x32x16_bf16 v[2:17], v[232:235], v[74:77], v[2:17]
	v_add_f32_e32 v1, v1, v230
	v_add_f32_e32 v227, v227, v1
	s_andn2_b64 vcc, exec, s[16:17]
	s_cbranch_vccnz .LBB0_1449

; __global__ void __launch_bounds__(512, 2) mk_fwd(Args args) {
	.amdhsa_kernel _Z6mk_fwd4Args
		.amdhsa_group_segment_fixed_size 0
		.amdhsa_private_segment_fixed_size 0
		.amdhsa_kernarg_size 448
		.amdhsa_user_sgpr_count 2
		.amdhsa_user_sgpr_dispatch_ptr 0
		.amdhsa_user_sgpr_queue_ptr 0
		.amdhsa_user_sgpr_kernarg_segment_ptr 1
		.amdhsa_user_sgpr_dispatch_id 0
		.amdhsa_user_sgpr_kernarg_preload_length 0
		.amdhsa_user_sgpr_kernarg_preload_offset 0
		.amdhsa_user_sgpr_private_segment_size 0
		.amdhsa_uses_dynamic_stack 0
		.amdhsa_enable_private_segment 0
		.amdhsa_system_sgpr_workgroup_id_x 1
		.amdhsa_system_sgpr_workgroup_id_y 0
		.amdhsa_system_sgpr_workgroup_id_z 0
		.amdhsa_system_sgpr_workgroup_info 0
		.amdhsa_system_vgpr_workitem_id 2
		.amdhsa_next_free_vgpr 256
		.amdhsa_next_free_sgpr 102
		.amdhsa_accum_offset 256
		.amdhsa_reserve_vcc 1
		.amdhsa_float_round_mode_32 0
		.amdhsa_float_round_mode_16_64 0
		.amdhsa_float_denorm_mode_32 3
		.amdhsa_float_denorm_mode_16_64 3
		.amdhsa_dx10_clamp 1
		.amdhsa_ieee_mode 1
		.amdhsa_fp16_overflow 0
		.amdhsa_tg_split 0
		.amdhsa_exception_fp_ieee_invalid_op 0
		.amdhsa_exception_fp_denorm_src 0
		.amdhsa_exception_fp_ieee_div_zero 0
		.amdhsa_exception_fp_ieee_overflow 0
		.amdhsa_exception_fp_ieee_underflow 0
		.amdhsa_exception_fp_ieee_inexact 0
		.amdhsa_exception_int_div_zero 0
	.end_amdhsa_kernel

; __global__ void __launch_bounds__(512, 2) mk_fwd(Args args) {
amdhsa.kernels:
  - .agpr_count:     0
    .args:
      - .offset:         0
        .size:           192
        .value_kind:     by_value
      - .offset:         192
        .size:           4
        .value_kind:     hidden_block_count_x
      - .offset:         196
        .size:           4
        .value_kind:     hidden_block_count_y
      - .offset:         200
        .size:           4
        .value_kind:     hidden_block_count_z
      - .offset:         204
        .size:           2
        .value_kind:     hidden_group_size_x
      - .offset:         206
        .size:           2
        .value_kind:     hidden_group_size_y
      - .offset:         208
        .size:           2
        .value_kind:     hidden_group_size_z
      - .offset:         210
        .size:           2
        .value_kind:     hidden_remainder_x
      - .offset:         212
        .size:           2
        .value_kind:     hidden_remainder_y
      - .offset:         214
        .size:           2
        .value_kind:     hidden_remainder_z
      - .offset:         232
        .size:           8
        .value_kind:     hidden_global_offset_x
      - .offset:         240
        .size:           8
        .value_kind:     hidden_global_offset_y
      - .offset:         248
        .size:           8
        .value_kind:     hidden_global_offset_z
      - .offset:         256
        .size:           2
        .value_kind:     hidden_grid_dims
      - .offset:         280
        .size:           8
        .value_kind:     hidden_multigrid_sync_arg
      - .offset:         312
        .size:           4
        .value_kind:     hidden_dynamic_lds_size
    .group_segment_fixed_size: 0
    .kernarg_segment_align: 8
    .kernarg_segment_size: 448
    .language:       OpenCL C
    .language_version:
      - 2
      - 0
    .max_flat_workgroup_size: 512
    .name:           _Z6mk_fwd4Args
    .private_segment_fixed_size: 0
    .sgpr_count:     108
    .sgpr_spill_count: 46
    .symbol:         _Z6mk_fwd4Args.kd
    .uniform_work_group_size: 1
    .uses_dynamic_stack: false
    .vgpr_count:     256
    .vgpr_spill_count: 0
    .wavefront_size: 64
